# sattn batched + sconv item loads batched (28 loads per item in one batch, consumers renamed)
# speedup vs baseline: 1.0031x; 1.0031x over previous
; __device__ __forceinline__ void sconv_item(const Args& args, int l, int item, int lane) {
;     asm volatile("" : "+v"(lane));
;     unsigned char* ws = args.ws;
;     const bf16_t* PROJ = (const bf16_t*)(ws + WS_PROJ); bf16_t* ACONV = (bf16_t*)(ws + WS_ABR + SZ_ABR1);
;     const int tb = item >> 1, c0 = (item & 1) * 512 + lane * 8, row0 = tb * 8;
;     const bool smp = row0 >= MP;
;     const int b = smp ? (row0 - MP) / DSEQ : row0 / SEQ, t0 = smp ? (row0 - MP) % DSEQ : row0 % SEQ, T = smp ? DSEQ : SEQ;
.LBB0_686:
	s_add_i32 s23, s2, 0x4000
	s_and_b32 s6, s23, -8
	s_cmpk_gt_i32 s6, 0x3fff
	s_cselect_b64 s[0:1], -1, 0
	s_cmpk_lt_i32 s6, 0x4000
	s_cselect_b64 s[8:9], -1, 0
	v_mov_b32_e32 v2, v1
	s_mov_b64 s[16:17], -1
	s_and_b64 vcc, exec, s[8:9]
	s_cbranch_vccz .LBB0_690
	s_ashr_i32 s4, s6, 31
	s_lshr_b32 s4, s4, 19
	s_add_i32 s4, s6, s4
	s_ashr_i32 s4, s4, 13
	s_cbranch_execz .LBB0_691

; __device__ __forceinline__ void unpack8(u32x4 w, f32x4& a, f32x4& b) { a = (f32x4){bf_lo(w.x), bf_hi(w.x), bf_lo(w.y), bf_hi(w.y)}; b = (f32x4){bf_lo(w.z), bf_hi(w.z), bf_lo(w.w), bf_hi(w.w)}; }
; __device__ __forceinline__ void sconv_item(const Args& args, int l, int item, int lane) {
;     ...
;     const float* cw = args.in[I_SCW] + (size_t)l * 3 * LW + c0;
;     f32x4 w[3][2];
; #pragma unroll
;     for (int k = 0; k < 3; ++k) { w[k][0] = *(const f32x4*)(cw + k * LW); w[k][1] = *(const f32x4*)(cw + k * LW + 4); }
;     f32x4 zm2[2], zm1[2];
;     if (t0 > 0) {
;         f32x4 a0, a1, b0, b1;
;         unpack8(*(const u32x4*)(PROJ + (size_t)(row0 - 2) * INC + C_SC + c0), a0, a1); unpack8(*(const u32x4*)(PROJ + (size_t)(row0 - 2) * INC + C_SH + c0), b0, b1); zm2[0] = a0 * b0; zm2[1] = a1 * b1;
;         unpack8(*(const u32x4*)(PROJ + (size_t)(row0 - 1) * INC + C_SC + c0), a0, a1); unpack8(*(const u32x4*)(PROJ + (size_t)(row0 - 1) * INC + C_SH + c0), b0, b1); zm1[0] = a0 * b0; zm1[1] = a1 * b1;
;     } else if (smp) {
;         const float* sb = args.in[I_SSC] + ((size_t)l * DBATCH + b) * 2 * LW + c0;
;         zm2[0] = *(const f32x4*)sb; zm2[1] = *(const f32x4*)(sb + 4); zm1[0] = *(const f32x4*)(sb + LW); zm1[1] = *(const f32x4*)(sb + LW + 4);
;     } else { zm2[0] = (f32x4){0.f, 0.f, 0.f, 0.f}; zm2[1] = zm2[0]; zm1[0] = zm2[0]; zm1[1] = zm2[0]; }
; #pragma unroll
;     for (int i = 0; i < 8; ++i) {
;         const bf16_t* pr = PROJ + (size_t)(row0 + i) * INC + c0;
;         f32x4 a0, a1, b0, b1, s0, s1;
;         unpack8(*(const u32x4*)(pr + C_SC), a0, a1); unpack8(*(const u32x4*)(pr + C_SH), b0, b1); unpack8(*(const u32x4*)(pr + C_SB), s0, s1);
.LBB0_694:
	s_and_b32 s5, s3, 0x200
	v_lshl_add_u32 v42, v2, 3, s5
	v_lshlrev_b32_e32 v144, 1, v42
	s_mul_i32 s98, s6, 0x6000
	s_mul_hi_i32 s99, s6, 0x6000
	s_add_u32 s98, s98, s10
	s_addc_u32 s99, s99, s11
	s_add_u32 s98, s98, 0xffff5800
	s_addc_u32 s99, s99, -1
	global_load_dwordx4 v[80:83], v144, s[98:99]
	global_load_dwordx4 v[84:87], v144, s[98:99] offset:2048
	s_add_u32 s98, s98, 0x6000
	s_addc_u32 s99, s99, 0
	global_load_dwordx4 v[88:91], v144, s[98:99]
	global_load_dwordx4 v[92:95], v144, s[98:99] offset:2048
	s_add_u32 s98, s98, 0x6000
	s_addc_u32 s99, s99, 0
	global_load_dwordx4 v[96:99], v144, s[98:99]
	global_load_dwordx4 v[100:103], v144, s[98:99] offset:2048
	global_load_dwordx4 v[104:107], v144, s[98:99] offset:-2048
	s_add_u32 s98, s98, 0x6000
	s_addc_u32 s99, s99, 0
	global_load_dwordx4 v[108:111], v144, s[98:99]
	global_load_dwordx4 v[112:115], v144, s[98:99] offset:2048
	global_load_dwordx4 v[116:119], v144, s[98:99] offset:-2048
	s_add_u32 s98, s98, 0x6000
	s_addc_u32 s99, s99, 0
	global_load_dwordx4 v[120:123], v144, s[98:99]
	global_load_dwordx4 v[124:127], v144, s[98:99] offset:2048
	global_load_dwordx4 v[132:135], v144, s[98:99] offset:-2048
	s_add_u32 s98, s98, 0x6000
	s_addc_u32 s99, s99, 0
	global_load_dwordx4 v[136:139], v144, s[98:99]
	global_load_dwordx4 v[140:143], v144, s[98:99] offset:2048
	global_load_dwordx4 v[146:149], v144, s[98:99] offset:-2048
	s_add_u32 s98, s98, 0x6000
	s_addc_u32 s99, s99, 0
	global_load_dwordx4 v[150:153], v144, s[98:99]
	global_load_dwordx4 v[154:157], v144, s[98:99] offset:2048
	global_load_dwordx4 v[158:161], v144, s[98:99] offset:-2048
	s_add_u32 s98, s98, 0x6000
	s_addc_u32 s99, s99, 0
	global_load_dwordx4 v[162:165], v144, s[98:99]
	global_load_dwordx4 v[166:169], v144, s[98:99] offset:2048
	global_load_dwordx4 v[170:173], v144, s[98:99] offset:-2048
	s_add_u32 s98, s98, 0x6000
	s_addc_u32 s99, s99, 0
	global_load_dwordx4 v[174:177], v144, s[98:99]
	global_load_dwordx4 v[178:181], v144, s[98:99] offset:2048
	global_load_dwordx4 v[182:185], v144, s[98:99] offset:-2048
	s_add_u32 s98, s98, 0x6000
	s_addc_u32 s99, s99, 0
	global_load_dwordx4 v[186:189], v144, s[98:99]
	global_load_dwordx4 v[190:193], v144, s[98:99] offset:2048
	global_load_dwordx4 v[194:197], v144, s[98:99] offset:-2048
	v_ashrrev_i32_e32 v43, 31, v42
	s_waitcnt lgkmcnt(0)
	v_lshl_add_u64 v[2:3], v[42:43], 2, s[30:31]
	s_mov_b64 s[8:9], 0x1000
	v_add_co_u32_e32 v6, vcc, 0x1000, v2
	v_lshl_add_u64 v[4:5], v[2:3], 0, s[8:9]
	s_nop 0
	v_addc_co_u32_e32 v7, vcc, 0, v3, vcc
	s_mov_b64 s[8:9], 0x2000
	global_load_dwordx4 v[10:13], v[2:3], off offset:16
	global_load_dwordx4 v[14:17], v[2:3], off
	global_load_dwordx4 v[22:25], v[6:7], off
	global_load_dwordx4 v[18:21], v[4:5], off offset:16
	v_lshl_add_u64 v[4:5], v[2:3], 0, s[8:9]
	v_add_co_u32_e32 v2, vcc, 0x2000, v2
	s_cmp_lt_i32 s22, 1
	s_nop 0
	v_addc_co_u32_e32 v3, vcc, 0, v3, vcc
	global_load_dwordx4 v[6:9], v[2:3], off
	s_nop 0
	global_load_dwordx4 v[2:5], v[4:5], off offset:16
	s_mov_b64 s[8:9], -1
	s_cbranch_scc0 .LBB0_698
	v_mov_b32_e32 v37, 0
	s_andn2_b64 vcc, exec, s[0:1]
	v_mov_b32_e32 v36, 0
	v_mov_b32_e32 v35, 0
	v_mov_b32_e32 v34, 0
	v_mov_b32_e32 v41, 0
	v_mov_b32_e32 v40, 0
	v_mov_b32_e32 v39, 0
	v_mov_b32_e32 v38, 0
	v_mov_b32_e32 v33, 0
	v_mov_b32_e32 v32, 0
	v_mov_b32_e32 v31, 0
	v_mov_b32_e32 v30, 0
	v_mov_b32_e32 v29, 0
	v_mov_b32_e32 v28, 0
	v_mov_b32_e32 v27, 0
	v_mov_b32_e32 v26, 0
	s_cbranch_vccnz .LBB0_697
	s_ashr_i32 s5, s4, 31
	s_lshl_b64 s[8:9], s[4:5], 13
	s_add_u32 s8, s26, s8
	s_addc_u32 s9, s27, s9
	v_lshl_add_u64 v[26:27], v[42:43], 2, s[8:9]
	s_mov_b64 s[8:9], 0x1000
	global_load_dwordx4 v[38:41], v[26:27], off
	global_load_dwordx4 v[34:37], v[26:27], off offset:16
	v_lshl_add_u64 v[30:31], v[26:27], 0, s[8:9]
	v_add_co_u32_e32 v26, vcc, 0x1000, v26
	s_nop 1
	v_addc_co_u32_e32 v27, vcc, 0, v27, vcc
	global_load_dwordx4 v[26:29], v[26:27], off
	s_nop 0
	global_load_dwordx4 v[30:33], v[30:31], off offset:16

; __device__ __forceinline__ u32x4 pack8(f32x4 a, f32x4 b) { u32x4 w; w.x = cvtpk(a[0], a[1]); w.y = cvtpk(a[2], a[3]); w.z = cvtpk(b[0], b[1]); w.w = cvtpk(b[2], b[3]); return w; }
; __device__ __forceinline__ void unpack8(u32x4 w, f32x4& a, f32x4& b) { a = (f32x4){bf_lo(w.x), bf_hi(w.x), bf_lo(w.y), bf_hi(w.y)}; b = (f32x4){bf_lo(w.z), bf_hi(w.z), bf_lo(w.w), bf_hi(w.w)}; }
; __device__ __forceinline__ void sconv_item(const Args& args, int l, int item, int lane) {
;     ...
;     if (t0 > 0) {
;         f32x4 a0, a1, b0, b1;
;         unpack8(*(const u32x4*)(PROJ + (size_t)(row0 - 2) * INC + C_SC + c0), a0, a1); unpack8(*(const u32x4*)(PROJ + (size_t)(row0 - 2) * INC + C_SH + c0), b0, b1); zm2[0] = a0 * b0; zm2[1] = a1 * b1;
;         unpack8(*(const u32x4*)(PROJ + (size_t)(row0 - 1) * INC + C_SC + c0), a0, a1); unpack8(*(const u32x4*)(PROJ + (size_t)(row0 - 1) * INC + C_SH + c0), b0, b1); zm1[0] = a0 * b0; zm1[1] = a1 * b1;
;     } else if (smp) {
;         const float* sb = args.in[I_SSC] + ((size_t)l * DBATCH + b) * 2 * LW + c0;
;         zm2[0] = *(const f32x4*)sb; zm2[1] = *(const f32x4*)(sb + 4); zm1[0] = *(const f32x4*)(sb + LW); zm1[1] = *(const f32x4*)(sb + LW + 4);
;     } else { zm2[0] = (f32x4){0.f, 0.f, 0.f, 0.f}; zm2[1] = zm2[0]; zm1[0] = zm2[0]; zm1[1] = zm2[0]; }
; #pragma unroll
;     for (int i = 0; i < 8; ++i) {
;         const bf16_t* pr = PROJ + (size_t)(row0 + i) * INC + c0;
;         f32x4 a0, a1, b0, b1, s0, s1;
;         unpack8(*(const u32x4*)(pr + C_SC), a0, a1); unpack8(*(const u32x4*)(pr + C_SH), b0, b1); unpack8(*(const u32x4*)(pr + C_SB), s0, s1);
;         const f32x4 z0 = a0 * b0, z1 = a1 * b1;
;         const f32x4 cv0 = w[0][0] * zm2[0] + w[1][0] * zm1[0] + w[2][0] * z0, cv1 = w[0][1] * zm2[1] + w[1][1] * zm1[1] + w[2][1] * z1;
;         *(u32x4*)(ACONV + (size_t)(row0 + i) * LW + c0) = pack8(s0 * cv0, s1 * cv1);
;         zm2[0] = zm1[0]; zm2[1] = zm1[1]; zm1[0] = z0; zm1[1] = z1;
.LBB0_698:
	s_andn2_b64 vcc, exec, s[8:9]
	v_lshlrev_b64 v[46:47], 1, v[42:43]
	s_cbranch_vccnz .LBB0_700
	s_mul_i32 s5, s6, 0x6000
	s_add_i32 s7, s6, -2
	s_add_i32 s8, s5, 0xffff4000
	s_mul_hi_i32 s7, s7, 0x6000
	s_add_u32 s8, s10, s8
	s_addc_u32 s9, s11, s7
	s_waitcnt vmcnt(0)
	v_lshl_add_u64 v[30:31], s[8:9], 0, v[46:47]
	v_add_co_u32_e32 v26, vcc, 0x1000, v30
	s_movk_i32 s16, 0x2000
	s_nop 0
	v_addc_co_u32_e32 v27, vcc, 0, v31, vcc
	s_add_i32 s7, s6, -1
	s_addk_i32 s5, 0xa000
	s_mul_hi_i32 s7, s7, 0x6000
	s_add_u32 s8, s10, s5
	s_addc_u32 s9, s11, s7
	s_movk_i32 s5, 0x1000
	s_waitcnt vmcnt(0)
	v_lshlrev_b32_e32 v32, 16, v80
	v_and_b32_e32 v33, 0xffff0000, v80
	v_add_co_u32_e32 v26, vcc, s16, v30
	v_lshlrev_b32_e32 v34, 16, v81
	v_and_b32_e32 v35, 0xffff0000, v81
	v_addc_co_u32_e32 v27, vcc, 0, v31, vcc
	v_lshlrev_b32_e32 v44, 16, v82
	v_and_b32_e32 v45, 0xffff0000, v82
	v_lshlrev_b32_e32 v36, 16, v83
	v_and_b32_e32 v37, 0xffff0000, v83
	s_waitcnt vmcnt(0)
	v_lshlrev_b32_e32 v30, 16, v84
	v_and_b32_e32 v31, 0xffff0000, v84
	v_lshlrev_b32_e32 v26, 16, v85
	v_and_b32_e32 v27, 0xffff0000, v85
	v_pk_mul_f32 v[38:39], v[32:33], v[30:31]
	v_lshl_add_u64 v[30:31], s[8:9], 0, v[46:47]
	v_pk_mul_f32 v[40:41], v[34:35], v[26:27]
	v_add_co_u32_e32 v26, vcc, s5, v30
	v_lshlrev_b32_e32 v48, 16, v86
	v_and_b32_e32 v49, 0xffff0000, v86
	v_lshlrev_b32_e32 v28, 16, v87
	v_and_b32_e32 v29, 0xffff0000, v87
	v_addc_co_u32_e32 v27, vcc, 0, v31, vcc
	v_pk_mul_f32 v[36:37], v[36:37], v[28:29]
	v_pk_mul_f32 v[34:35], v[44:45], v[48:49]
	s_waitcnt vmcnt(0)
	v_lshlrev_b32_e32 v32, 16, v88
	v_and_b32_e32 v33, 0xffff0000, v88
	v_add_co_u32_e32 v26, vcc, s16, v30
	v_lshlrev_b32_e32 v44, 16, v89
	v_and_b32_e32 v45, 0xffff0000, v89
	v_addc_co_u32_e32 v27, vcc, 0, v31, vcc
	v_lshlrev_b32_e32 v48, 16, v90
	v_and_b32_e32 v49, 0xffff0000, v90
	v_lshlrev_b32_e32 v50, 16, v91
	v_and_b32_e32 v51, 0xffff0000, v91
	s_waitcnt vmcnt(0)
	v_lshlrev_b32_e32 v30, 16, v92
	v_and_b32_e32 v31, 0xffff0000, v92
	v_lshlrev_b32_e32 v26, 16, v93
	v_and_b32_e32 v27, 0xffff0000, v93
	v_lshlrev_b32_e32 v52, 16, v94
	v_and_b32_e32 v53, 0xffff0000, v94
	v_lshlrev_b32_e32 v54, 16, v95
	v_and_b32_e32 v55, 0xffff0000, v95
	v_pk_mul_f32 v[28:29], v[44:45], v[26:27]
	v_pk_mul_f32 v[26:27], v[32:33], v[30:31]
	v_pk_mul_f32 v[32:33], v[50:51], v[54:55]
	v_pk_mul_f32 v[30:31], v[48:49], v[52:53]
.LBB0_700:
	v_lshl_add_u64 v[44:45], s[10:11], 0, v[46:47]
	v_mad_i64_i32 v[52:53], s[8:9], s6, v206, v[44:45]
	s_movk_i32 s36, 0x1000
	v_add_co_u32_e32 v56, vcc, s36, v52
	s_movk_i32 s5, 0x2000
	s_nop 0
	v_addc_co_u32_e32 v57, vcc, 0, v53, vcc
	v_add_co_u32_e32 v52, vcc, s5, v52
	s_nop 0
	v_addc_co_u32_e32 v53, vcc, 0, v53, vcc
	s_nop 0
	s_waitcnt vmcnt(3)
	v_pk_mul_f32 v[40:41], v[16:17], v[40:41]
	v_pk_mul_f32 v[38:39], v[14:15], v[38:39]
	s_waitcnt vmcnt(2)
	v_pk_mul_f32 v[34:35], v[10:11], v[34:35]
	v_pk_mul_f32 v[36:37], v[12:13], v[36:37]
	s_waitcnt vmcnt(1)
	v_pk_fma_f32 v[60:61], v[24:25], v[28:29], v[40:41]
	v_pk_fma_f32 v[62:63], v[22:23], v[26:27], v[38:39]
	s_waitcnt vmcnt(0)
	v_pk_fma_f32 v[64:65], v[20:21], v[32:33], v[36:37]
	v_pk_fma_f32 v[66:67], v[18:19], v[30:31], v[34:35]
	v_readlane_b32 s8, v251, 62
	s_or_b32 s16, s6, 1
	v_readlane_b32 s9, v251, 63
	s_ashr_i32 s7, s6, 31
	v_mad_i64_i32 v[68:69], s[24:25], s16, v206, v[44:45]
	v_lshl_add_u64 v[46:47], s[8:9], 0, v[46:47]
	s_lshl_b64 s[8:9], s[6:7], 11
	v_add_co_u32_e32 v72, vcc, s36, v68
	v_lshl_add_u64 v[70:71], v[46:47], 0, s[8:9]
	s_nop 0
	v_addc_co_u32_e32 v73, vcc, 0, v69, vcc
	s_or_b32 s8, s6, 2
	s_ashr_i32 s17, s16, 31
	s_lshl_b64 s[16:17], s[16:17], 11
	s_or_b32 s6, s6, 3
	s_ashr_i32 s9, s8, 31
	s_ashr_i32 s7, s6, 31
	v_lshlrev_b32_e32 v36, 16, v96
	v_and_b32_e32 v37, 0xffff0000, v96
	v_lshlrev_b32_e32 v34, 16, v97
	v_and_b32_e32 v35, 0xffff0000, v97
	v_lshlrev_b32_e32 v40, 16, v98
	v_and_b32_e32 v41, 0xffff0000, v98
	v_lshlrev_b32_e32 v38, 16, v99
	v_and_b32_e32 v39, 0xffff0000, v99
	v_lshlrev_b32_e32 v48, 16, v100
	v_and_b32_e32 v49, 0xffff0000, v100
	v_lshlrev_b32_e32 v50, 16, v101
	v_and_b32_e32 v51, 0xffff0000, v101
	v_lshlrev_b32_e32 v52, 16, v102
	v_and_b32_e32 v53, 0xffff0000, v102
	v_lshlrev_b32_e32 v54, 16, v103
	v_and_b32_e32 v55, 0xffff0000, v103
	v_pk_mul_f32 v[34:35], v[34:35], v[50:51]
	v_pk_mul_f32 v[36:37], v[36:37], v[48:49]
	v_pk_mul_f32 v[38:39], v[38:39], v[54:55]
	v_pk_mul_f32 v[40:41], v[40:41], v[52:53]
	v_lshlrev_b32_e32 v74, 16, v104
	v_and_b32_e32 v75, 0xffff0000, v104
	v_lshlrev_b32_e32 v56, 16, v105
	v_and_b32_e32 v57, 0xffff0000, v105
	v_lshlrev_b32_e32 v76, 16, v106
	v_and_b32_e32 v77, 0xffff0000, v106
	v_lshlrev_b32_e32 v58, 16, v107
	v_and_b32_e32 v59, 0xffff0000, v107
	v_pk_fma_f32 v[48:49], v[6:7], v[36:37], v[62:63]
	v_pk_fma_f32 v[50:51], v[8:9], v[34:35], v[60:61]
	v_pk_fma_f32 v[52:53], v[2:3], v[40:41], v[66:67]
	v_pk_fma_f32 v[54:55], v[4:5], v[38:39], v[64:65]
	v_pk_mul_f32 v[50:51], v[50:51], v[56:57]
	v_pk_mul_f32 v[48:49], v[48:49], v[74:75]
	v_pk_mul_f32 v[54:55], v[54:55], v[58:59]
	v_pk_mul_f32 v[52:53], v[52:53], v[76:77]
	v_cvt_pk_bf16_f32 v48, v48, v49
	v_cvt_pk_bf16_f32 v49, v50, v51
	v_cvt_pk_bf16_f32 v50, v52, v53
	v_cvt_pk_bf16_f32 v51, v54, v55
	global_store_dwordx4 v[70:71], v[48:51], off
	v_add_co_u32_e32 v52, vcc, s5, v68
	s_nop 0
	v_addc_co_u32_e32 v53, vcc, 0, v69, vcc
	s_nop 0
	v_pk_mul_f32 v[66:67], v[22:23], v[36:37]
	v_pk_mul_f32 v[68:69], v[24:25], v[34:35]
	v_pk_mul_f32 v[70:71], v[18:19], v[40:41]
	v_pk_mul_f32 v[72:73], v[20:21], v[38:39]
	v_pk_fma_f32 v[68:69], v[16:17], v[28:29], v[68:69]
	v_pk_fma_f32 v[66:67], v[14:15], v[26:27], v[66:67]
; __device__ __forceinline__ u32x4 pack8(f32x4 a, f32x4 b) { u32x4 w; w.x = cvtpk(a[0], a[1]); w.y = cvtpk(a[2], a[3]); w.z = cvtpk(b[0], b[1]); w.w = cvtpk(b[2], b[3]); return w; }
; __device__ __forceinline__ void unpack8(u32x4 w, f32x4& a, f32x4& b) { a = (f32x4){bf_lo(w.x), bf_hi(w.x), bf_lo(w.y), bf_hi(w.y)}; b = (f32x4){bf_lo(w.z), bf_hi(w.z), bf_lo(w.w), bf_hi(w.w)}; }
; __device__ __forceinline__ void sconv_item(const Args& args, int l, int item, int lane) {
;     ...
; #pragma unroll
;     for (int i = 0; i < 8; ++i) {
;         const bf16_t* pr = PROJ + (size_t)(row0 + i) * INC + c0;
;         f32x4 a0, a1, b0, b1, s0, s1;
;         unpack8(*(const u32x4*)(pr + C_SC), a0, a1); unpack8(*(const u32x4*)(pr + C_SH), b0, b1); unpack8(*(const u32x4*)(pr + C_SB), s0, s1);
;         const f32x4 z0 = a0 * b0, z1 = a1 * b1;
;         const f32x4 cv0 = w[0][0] * zm2[0] + w[1][0] * zm1[0] + w[2][0] * z0, cv1 = w[0][1] * zm2[1] + w[1][1] * zm1[1] + w[2][1] * z1;
;         *(u32x4*)(ACONV + (size_t)(row0 + i) * LW + c0) = pack8(s0 * cv0, s1 * cv1);
;         zm2[0] = zm1[0]; zm2[1] = zm1[1]; zm1[0] = z0; zm1[1] = z1;
	v_pk_fma_f32 v[72:73], v[12:13], v[32:33], v[72:73]
	v_pk_fma_f32 v[70:71], v[10:11], v[30:31], v[70:71]
	v_mad_i64_i32 v[60:61], s[24:25], s8, v206, v[44:45]
	v_add_co_u32_e32 v62, vcc, s36, v60
	v_lshl_add_u64 v[64:65], v[46:47], 0, s[16:17]
	s_nop 0
	v_addc_co_u32_e32 v63, vcc, 0, v61, vcc
	s_lshl_b64 s[8:9], s[8:9], 11
	v_lshlrev_b32_e32 v28, 16, v108
	v_and_b32_e32 v29, 0xffff0000, v108
	v_lshlrev_b32_e32 v26, 16, v109
	v_and_b32_e32 v27, 0xffff0000, v109
	v_lshlrev_b32_e32 v32, 16, v110
	v_and_b32_e32 v33, 0xffff0000, v110
	v_lshlrev_b32_e32 v30, 16, v111
	v_and_b32_e32 v31, 0xffff0000, v111
	v_lshlrev_b32_e32 v48, 16, v112
	v_and_b32_e32 v49, 0xffff0000, v112
	v_lshlrev_b32_e32 v50, 16, v113
	v_and_b32_e32 v51, 0xffff0000, v113
	v_lshlrev_b32_e32 v52, 16, v114
	v_and_b32_e32 v53, 0xffff0000, v114
	v_lshlrev_b32_e32 v54, 16, v115
	v_and_b32_e32 v55, 0xffff0000, v115
	v_pk_mul_f32 v[26:27], v[26:27], v[50:51]
	v_pk_mul_f32 v[28:29], v[28:29], v[48:49]
	v_pk_mul_f32 v[30:31], v[30:31], v[54:55]
	v_pk_mul_f32 v[32:33], v[32:33], v[52:53]
	v_lshlrev_b32_e32 v74, 16, v116
	v_and_b32_e32 v75, 0xffff0000, v116
	v_lshlrev_b32_e32 v56, 16, v117
	v_and_b32_e32 v57, 0xffff0000, v117
	v_lshlrev_b32_e32 v76, 16, v118
	v_and_b32_e32 v77, 0xffff0000, v118
	v_lshlrev_b32_e32 v58, 16, v119
	v_and_b32_e32 v59, 0xffff0000, v119
	v_pk_fma_f32 v[48:49], v[6:7], v[28:29], v[66:67]
	v_pk_fma_f32 v[50:51], v[8:9], v[26:27], v[68:69]
	v_pk_fma_f32 v[52:53], v[2:3], v[32:33], v[70:71]
	v_pk_fma_f32 v[54:55], v[4:5], v[30:31], v[72:73]
	v_pk_mul_f32 v[50:51], v[50:51], v[56:57]
	v_pk_mul_f32 v[48:49], v[48:49], v[74:75]
	v_pk_mul_f32 v[54:55], v[54:55], v[58:59]
	v_pk_mul_f32 v[52:53], v[52:53], v[76:77]
	v_cvt_pk_bf16_f32 v48, v48, v49
	v_cvt_pk_bf16_f32 v49, v50, v51
	v_cvt_pk_bf16_f32 v50, v52, v53
	v_cvt_pk_bf16_f32 v51, v54, v55
	global_store_dwordx4 v[64:65], v[48:51], off
	v_add_co_u32_e32 v52, vcc, s5, v60
	s_nop 0
	v_addc_co_u32_e32 v53, vcc, 0, v61, vcc
	s_nop 0
	v_pk_mul_f32 v[66:67], v[22:23], v[28:29]
	v_pk_mul_f32 v[68:69], v[24:25], v[26:27]
	v_pk_mul_f32 v[70:71], v[18:19], v[32:33]
	v_pk_mul_f32 v[72:73], v[20:21], v[30:31]
	v_pk_fma_f32 v[34:35], v[16:17], v[34:35], v[68:69]
	v_pk_fma_f32 v[66:67], v[14:15], v[36:37], v[66:67]
	v_pk_fma_f32 v[68:69], v[12:13], v[38:39], v[72:73]
	v_pk_fma_f32 v[70:71], v[10:11], v[40:41], v[70:71]
	v_mad_i64_i32 v[60:61], s[16:17], s6, v206, v[44:45]
	v_add_co_u32_e32 v62, vcc, s36, v60
	v_lshl_add_u64 v[64:65], v[46:47], 0, s[8:9]
	s_nop 0
	v_addc_co_u32_e32 v63, vcc, 0, v61, vcc
	s_or_b32 s8, s23, 4
	s_lshl_b64 s[6:7], s[6:7], 11
	s_ashr_i32 s9, s8, 31
	v_lshlrev_b32_e32 v38, 16, v120
	v_and_b32_e32 v39, 0xffff0000, v120
	v_lshlrev_b32_e32 v36, 16, v121
	v_and_b32_e32 v37, 0xffff0000, v121
	v_lshlrev_b32_e32 v48, 16, v122
	v_and_b32_e32 v49, 0xffff0000, v122
	v_lshlrev_b32_e32 v40, 16, v123
	v_and_b32_e32 v41, 0xffff0000, v123
	v_lshlrev_b32_e32 v50, 16, v124
	v_and_b32_e32 v51, 0xffff0000, v124
	v_lshlrev_b32_e32 v52, 16, v125
	v_and_b32_e32 v53, 0xffff0000, v125
	v_lshlrev_b32_e32 v72, 16, v126
	v_and_b32_e32 v73, 0xffff0000, v126
	v_lshlrev_b32_e32 v54, 16, v127
	v_and_b32_e32 v55, 0xffff0000, v127
	v_pk_mul_f32 v[36:37], v[36:37], v[52:53]
	v_pk_mul_f32 v[38:39], v[38:39], v[50:51]
	v_pk_mul_f32 v[40:41], v[40:41], v[54:55]
	v_pk_mul_f32 v[48:49], v[48:49], v[72:73]
	v_lshlrev_b32_e32 v74, 16, v132
	v_and_b32_e32 v75, 0xffff0000, v132
	v_lshlrev_b32_e32 v56, 16, v133
	v_and_b32_e32 v57, 0xffff0000, v133
	v_lshlrev_b32_e32 v76, 16, v134
	v_and_b32_e32 v77, 0xffff0000, v134
	v_lshlrev_b32_e32 v58, 16, v135
	v_and_b32_e32 v59, 0xffff0000, v135
	v_pk_fma_f32 v[50:51], v[6:7], v[38:39], v[66:67]
	v_pk_fma_f32 v[34:35], v[8:9], v[36:37], v[34:35]
	v_pk_fma_f32 v[52:53], v[2:3], v[48:49], v[70:71]
	v_pk_fma_f32 v[54:55], v[4:5], v[40:41], v[68:69]
	v_pk_mul_f32 v[34:35], v[34:35], v[56:57]
	v_pk_mul_f32 v[50:51], v[50:51], v[74:75]
	v_pk_mul_f32 v[54:55], v[54:55], v[58:59]
	v_pk_mul_f32 v[52:53], v[52:53], v[76:77]
	v_cvt_pk_bf16_f32 v50, v50, v51
	v_cvt_pk_bf16_f32 v51, v34, v35
	v_cvt_pk_bf16_f32 v52, v52, v53
	v_cvt_pk_bf16_f32 v53, v54, v55
	global_store_dwordx4 v[64:65], v[50:53], off
	v_add_co_u32_e32 v34, vcc, s5, v60
	s_nop 0
	v_addc_co_u32_e32 v35, vcc, 0, v61, vcc
	v_pk_mul_f32 v[66:67], v[22:23], v[38:39]
	v_pk_mul_f32 v[68:69], v[24:25], v[36:37]
	v_pk_mul_f32 v[70:71], v[18:19], v[48:49]
	v_pk_mul_f32 v[72:73], v[20:21], v[40:41]
	v_pk_fma_f32 v[26:27], v[16:17], v[26:27], v[68:69]
	v_pk_fma_f32 v[28:29], v[14:15], v[28:29], v[66:67]
	v_pk_fma_f32 v[30:31], v[12:13], v[30:31], v[72:73]
	v_pk_fma_f32 v[32:33], v[10:11], v[32:33], v[70:71]
	v_mad_i64_i32 v[34:35], s[16:17], s8, v206, v[44:45]
	v_add_co_u32_e32 v62, vcc, s36, v34
	v_lshl_add_u64 v[64:65], v[46:47], 0, s[6:7]
	s_nop 0
	v_addc_co_u32_e32 v63, vcc, 0, v35, vcc
	s_or_b32 s6, s23, 5
	s_lshl_b64 s[8:9], s[8:9], 11
	s_ashr_i32 s7, s6, 31
	v_lshlrev_b32_e32 v66, 16, v136
	v_and_b32_e32 v67, 0xffff0000, v136
	v_lshlrev_b32_e32 v50, 16, v137
	v_and_b32_e32 v51, 0xffff0000, v137
	v_lshlrev_b32_e32 v68, 16, v138
	v_and_b32_e32 v69, 0xffff0000, v138
	v_lshlrev_b32_e32 v70, 16, v139
	v_and_b32_e32 v71, 0xffff0000, v139
	v_lshlrev_b32_e32 v52, 16, v140
	v_and_b32_e32 v53, 0xffff0000, v140
	v_lshlrev_b32_e32 v54, 16, v141
	v_and_b32_e32 v55, 0xffff0000, v141
	v_lshlrev_b32_e32 v72, 16, v142
	v_and_b32_e32 v73, 0xffff0000, v142
	v_lshlrev_b32_e32 v56, 16, v143
	v_and_b32_e32 v57, 0xffff0000, v143
	v_pk_mul_f32 v[50:51], v[50:51], v[54:55]
	v_pk_mul_f32 v[52:53], v[66:67], v[52:53]
	v_pk_mul_f32 v[54:55], v[70:71], v[56:57]
; __device__ __forceinline__ u32x4 pack8(f32x4 a, f32x4 b) { u32x4 w; w.x = cvtpk(a[0], a[1]); w.y = cvtpk(a[2], a[3]); w.z = cvtpk(b[0], b[1]); w.w = cvtpk(b[2], b[3]); return w; }
; __device__ __forceinline__ void unpack8(u32x4 w, f32x4& a, f32x4& b) { a = (f32x4){bf_lo(w.x), bf_hi(w.x), bf_lo(w.y), bf_hi(w.y)}; b = (f32x4){bf_lo(w.z), bf_hi(w.z), bf_lo(w.w), bf_hi(w.w)}; }
; __device__ __forceinline__ void sconv_item(const Args& args, int l, int item, int lane) {
;     ...
; #pragma unroll
;     for (int i = 0; i < 8; ++i) {
;         const bf16_t* pr = PROJ + (size_t)(row0 + i) * INC + c0;
;         f32x4 a0, a1, b0, b1, s0, s1;
;         unpack8(*(const u32x4*)(pr + C_SC), a0, a1); unpack8(*(const u32x4*)(pr + C_SH), b0, b1); unpack8(*(const u32x4*)(pr + C_SB), s0, s1);
;         const f32x4 z0 = a0 * b0, z1 = a1 * b1;
;         const f32x4 cv0 = w[0][0] * zm2[0] + w[1][0] * zm1[0] + w[2][0] * z0, cv1 = w[0][1] * zm2[1] + w[1][1] * zm1[1] + w[2][1] * z1;
;         *(u32x4*)(ACONV + (size_t)(row0 + i) * LW + c0) = pack8(s0 * cv0, s1 * cv1);
;         zm2[0] = zm1[0]; zm2[1] = zm1[1]; zm1[0] = z0; zm1[1] = z1;
	v_pk_mul_f32 v[56:57], v[68:69], v[72:73]
	v_lshlrev_b32_e32 v74, 16, v146
	v_and_b32_e32 v75, 0xffff0000, v146
	v_lshlrev_b32_e32 v58, 16, v147
	v_and_b32_e32 v59, 0xffff0000, v147
	v_lshlrev_b32_e32 v76, 16, v148
	v_and_b32_e32 v77, 0xffff0000, v148
	v_lshlrev_b32_e32 v60, 16, v149
	v_and_b32_e32 v61, 0xffff0000, v149
	v_pk_fma_f32 v[28:29], v[6:7], v[52:53], v[28:29]
	v_pk_fma_f32 v[26:27], v[8:9], v[50:51], v[26:27]
	v_pk_fma_f32 v[32:33], v[2:3], v[56:57], v[32:33]
	v_pk_fma_f32 v[30:31], v[4:5], v[54:55], v[30:31]
	v_pk_mul_f32 v[58:59], v[26:27], v[58:59]
	v_pk_mul_f32 v[26:27], v[28:29], v[74:75]
	v_pk_mul_f32 v[30:31], v[30:31], v[60:61]
	v_pk_mul_f32 v[28:29], v[32:33], v[76:77]
	v_cvt_pk_bf16_f32 v26, v26, v27
	v_cvt_pk_bf16_f32 v27, v58, v59
	v_cvt_pk_bf16_f32 v28, v28, v29
	v_cvt_pk_bf16_f32 v29, v30, v31
	global_store_dwordx4 v[64:65], v[26:29], off
	v_add_co_u32_e32 v30, vcc, s5, v34
	s_nop 0
	v_addc_co_u32_e32 v31, vcc, 0, v35, vcc
	s_nop 0
	v_pk_mul_f32 v[66:67], v[22:23], v[52:53]
	v_pk_mul_f32 v[68:69], v[24:25], v[50:51]
	v_pk_mul_f32 v[70:71], v[18:19], v[56:57]
	v_pk_mul_f32 v[72:73], v[20:21], v[54:55]
	v_pk_fma_f32 v[36:37], v[16:17], v[36:37], v[68:69]
	v_pk_fma_f32 v[38:39], v[14:15], v[38:39], v[66:67]
	v_pk_fma_f32 v[40:41], v[12:13], v[40:41], v[72:73]
	v_pk_fma_f32 v[48:49], v[10:11], v[48:49], v[70:71]
	v_mad_i64_i32 v[34:35], s[16:17], s6, v206, v[44:45]
	v_add_co_u32_e32 v62, vcc, s36, v34
	v_lshl_add_u64 v[64:65], v[46:47], 0, s[8:9]
	s_nop 0
	v_addc_co_u32_e32 v63, vcc, 0, v35, vcc
	s_or_b32 s8, s23, 6
	s_ashr_i32 s9, s8, 31
	v_lshlrev_b32_e32 v66, 16, v150
	v_and_b32_e32 v67, 0xffff0000, v150
	v_lshlrev_b32_e32 v26, 16, v151
	v_and_b32_e32 v27, 0xffff0000, v151
	v_lshlrev_b32_e32 v68, 16, v152
	v_and_b32_e32 v69, 0xffff0000, v152
	v_lshlrev_b32_e32 v70, 16, v153
	v_and_b32_e32 v71, 0xffff0000, v153
	v_lshlrev_b32_e32 v28, 16, v154
	v_and_b32_e32 v29, 0xffff0000, v154
	v_lshlrev_b32_e32 v30, 16, v155
	v_and_b32_e32 v31, 0xffff0000, v155
	v_lshlrev_b32_e32 v72, 16, v156
	v_and_b32_e32 v73, 0xffff0000, v156
	v_lshlrev_b32_e32 v32, 16, v157
	v_and_b32_e32 v33, 0xffff0000, v157
	v_pk_mul_f32 v[26:27], v[26:27], v[30:31]
	v_pk_mul_f32 v[28:29], v[66:67], v[28:29]
	v_pk_mul_f32 v[30:31], v[70:71], v[32:33]
	v_pk_mul_f32 v[32:33], v[68:69], v[72:73]
	v_lshlrev_b32_e32 v74, 16, v158
	v_and_b32_e32 v75, 0xffff0000, v158
	v_lshlrev_b32_e32 v58, 16, v159
	v_and_b32_e32 v59, 0xffff0000, v159
	v_lshlrev_b32_e32 v76, 16, v160
	v_and_b32_e32 v77, 0xffff0000, v160
	v_lshlrev_b32_e32 v60, 16, v161
	v_and_b32_e32 v61, 0xffff0000, v161
	v_pk_fma_f32 v[38:39], v[6:7], v[28:29], v[38:39]
	v_pk_fma_f32 v[36:37], v[8:9], v[26:27], v[36:37]
	v_pk_fma_f32 v[48:49], v[2:3], v[32:33], v[48:49]
	v_pk_fma_f32 v[40:41], v[4:5], v[30:31], v[40:41]
	v_pk_mul_f32 v[58:59], v[36:37], v[58:59]
	v_pk_mul_f32 v[36:37], v[38:39], v[74:75]
	v_pk_mul_f32 v[40:41], v[40:41], v[60:61]
	v_pk_mul_f32 v[38:39], v[48:49], v[76:77]
	v_cvt_pk_bf16_f32 v36, v36, v37
	v_cvt_pk_bf16_f32 v37, v58, v59
	v_cvt_pk_bf16_f32 v38, v38, v39
	v_cvt_pk_bf16_f32 v39, v40, v41
	global_store_dwordx4 v[64:65], v[36:39], off
	v_add_co_u32_e32 v40, vcc, s5, v34
	s_nop 0
	v_addc_co_u32_e32 v41, vcc, 0, v35, vcc
	s_nop 0
	v_pk_mul_f32 v[40:41], v[22:23], v[28:29]
	v_pk_mul_f32 v[48:49], v[24:25], v[26:27]
	v_pk_mul_f32 v[72:73], v[18:19], v[32:33]
	v_pk_mul_f32 v[74:75], v[20:21], v[30:31]
	v_pk_fma_f32 v[76:77], v[16:17], v[50:51], v[48:49]
	v_pk_fma_f32 v[52:53], v[14:15], v[52:53], v[40:41]
	v_pk_fma_f32 v[56:57], v[10:11], v[56:57], v[72:73]
	v_pk_fma_f32 v[54:55], v[12:13], v[54:55], v[74:75]
	v_mad_i64_i32 v[66:67], s[16:17], s8, v206, v[44:45]
	s_lshl_b64 s[16:17], s[6:7], 11
	v_add_co_u32_e32 v68, vcc, s36, v66
	v_lshl_add_u64 v[70:71], v[46:47], 0, s[16:17]
	s_nop 0
	v_addc_co_u32_e32 v69, vcc, 0, v67, vcc
	s_or_b32 s16, s23, 7
	s_lshl_b64 s[8:9], s[8:9], 11
	s_ashr_i32 s17, s16, 31
	v_lshlrev_b32_e32 v40, 16, v162
	v_and_b32_e32 v41, 0xffff0000, v162
	v_lshlrev_b32_e32 v36, 16, v163
	v_and_b32_e32 v37, 0xffff0000, v163
	v_lshlrev_b32_e32 v50, 16, v164
	v_and_b32_e32 v51, 0xffff0000, v164
	v_lshlrev_b32_e32 v48, 16, v165
	v_and_b32_e32 v49, 0xffff0000, v165
	v_lshlrev_b32_e32 v72, 16, v166
	v_and_b32_e32 v73, 0xffff0000, v166
	v_lshlrev_b32_e32 v38, 16, v167
	v_and_b32_e32 v39, 0xffff0000, v167
	v_lshlrev_b32_e32 v58, 16, v168
	v_and_b32_e32 v59, 0xffff0000, v168
	v_lshlrev_b32_e32 v60, 16, v169
	v_and_b32_e32 v61, 0xffff0000, v169
	v_pk_mul_f32 v[38:39], v[36:37], v[38:39]
	v_pk_mul_f32 v[40:41], v[40:41], v[72:73]
	v_pk_mul_f32 v[48:49], v[48:49], v[60:61]
	v_pk_mul_f32 v[50:51], v[50:51], v[58:59]
	v_lshlrev_b32_e32 v74, 16, v170
	v_and_b32_e32 v75, 0xffff0000, v170
	v_lshlrev_b32_e32 v62, 16, v171
	v_and_b32_e32 v63, 0xffff0000, v171
	v_lshlrev_b32_e32 v78, 16, v172
	v_and_b32_e32 v79, 0xffff0000, v172
	v_lshlrev_b32_e32 v64, 16, v173
	v_and_b32_e32 v65, 0xffff0000, v173
	v_pk_fma_f32 v[36:37], v[6:7], v[40:41], v[52:53]
	v_pk_fma_f32 v[52:53], v[8:9], v[38:39], v[76:77]
	v_pk_fma_f32 v[56:57], v[2:3], v[50:51], v[56:57]
	v_pk_fma_f32 v[54:55], v[4:5], v[48:49], v[54:55]
	v_pk_mul_f32 v[58:59], v[52:53], v[62:63]
	v_pk_mul_f32 v[36:37], v[36:37], v[74:75]
	v_pk_mul_f32 v[60:61], v[54:55], v[64:65]
	v_pk_mul_f32 v[54:55], v[56:57], v[78:79]
	v_cvt_pk_bf16_f32 v52, v36, v37
	v_cvt_pk_bf16_f32 v53, v58, v59
	v_cvt_pk_bf16_f32 v54, v54, v55
	v_cvt_pk_bf16_f32 v55, v60, v61
	global_store_dwordx4 v[70:71], v[52:55], off
	v_add_co_u32_e32 v36, vcc, s5, v66
	s_nop 0
	v_addc_co_u32_e32 v37, vcc, 0, v67, vcc
	v_pk_mul_f32 v[68:69], v[22:23], v[40:41]
; __device__ __forceinline__ u32x4 pack8(f32x4 a, f32x4 b) { u32x4 w; w.x = cvtpk(a[0], a[1]); w.y = cvtpk(a[2], a[3]); w.z = cvtpk(b[0], b[1]); w.w = cvtpk(b[2], b[3]); return w; }
; __device__ __forceinline__ void unpack8(u32x4 w, f32x4& a, f32x4& b) { a = (f32x4){bf_lo(w.x), bf_hi(w.x), bf_lo(w.y), bf_hi(w.y)}; b = (f32x4){bf_lo(w.z), bf_hi(w.z), bf_lo(w.w), bf_hi(w.w)}; }
; __device__ __forceinline__ void sconv_item(const Args& args, int l, int item, int lane) {
;     ...
; #pragma unroll
;     for (int i = 0; i < 8; ++i) {
;         const bf16_t* pr = PROJ + (size_t)(row0 + i) * INC + c0;
;         f32x4 a0, a1, b0, b1, s0, s1;
;         unpack8(*(const u32x4*)(pr + C_SC), a0, a1); unpack8(*(const u32x4*)(pr + C_SH), b0, b1); unpack8(*(const u32x4*)(pr + C_SB), s0, s1);
;         const f32x4 z0 = a0 * b0, z1 = a1 * b1;
;         const f32x4 cv0 = w[0][0] * zm2[0] + w[1][0] * zm1[0] + w[2][0] * z0, cv1 = w[0][1] * zm2[1] + w[1][1] * zm1[1] + w[2][1] * z1;
;         *(u32x4*)(ACONV + (size_t)(row0 + i) * LW + c0) = pack8(s0 * cv0, s1 * cv1);
;         zm2[0] = zm1[0]; zm2[1] = zm1[1]; zm1[0] = z0; zm1[1] = z1;
;     }
	v_pk_mul_f32 v[70:71], v[24:25], v[38:39]
	v_pk_mul_f32 v[72:73], v[18:19], v[50:51]
	v_pk_mul_f32 v[74:75], v[20:21], v[48:49]
	v_pk_fma_f32 v[70:71], v[16:17], v[26:27], v[70:71]
	v_pk_fma_f32 v[68:69], v[14:15], v[28:29], v[68:69]
	v_pk_fma_f32 v[74:75], v[12:13], v[30:31], v[74:75]
	v_pk_fma_f32 v[72:73], v[10:11], v[32:33], v[72:73]
	v_mad_i64_i32 v[36:37], s[24:25], s16, v206, v[44:45]
	v_add_co_u32_e32 v64, vcc, s36, v36
	v_lshl_add_u64 v[66:67], v[46:47], 0, s[8:9]
	s_nop 0
	v_addc_co_u32_e32 v65, vcc, 0, v37, vcc
	s_lshl_b64 s[8:9], s[16:17], 11
	v_lshl_add_u64 v[46:47], v[46:47], 0, s[8:9]
	v_lshlrev_b32_e32 v26, 16, v174
	v_and_b32_e32 v27, 0xffff0000, v174
	v_lshlrev_b32_e32 v28, 16, v175
	v_and_b32_e32 v29, 0xffff0000, v175
	v_lshlrev_b32_e32 v30, 16, v176
	v_and_b32_e32 v31, 0xffff0000, v176
	v_lshlrev_b32_e32 v32, 16, v177
	v_and_b32_e32 v33, 0xffff0000, v177
	v_lshlrev_b32_e32 v52, 16, v178
	v_and_b32_e32 v53, 0xffff0000, v178
	v_lshlrev_b32_e32 v54, 16, v179
	v_and_b32_e32 v55, 0xffff0000, v179
	v_lshlrev_b32_e32 v56, 16, v180
	v_and_b32_e32 v57, 0xffff0000, v180
	v_lshlrev_b32_e32 v58, 16, v181
	v_and_b32_e32 v59, 0xffff0000, v181
	v_pk_mul_f32 v[28:29], v[28:29], v[54:55]
	v_pk_mul_f32 v[26:27], v[26:27], v[52:53]
	v_pk_mul_f32 v[32:33], v[32:33], v[58:59]
	v_pk_mul_f32 v[30:31], v[30:31], v[56:57]
	v_lshlrev_b32_e32 v76, 16, v182
	v_and_b32_e32 v77, 0xffff0000, v182
	v_lshlrev_b32_e32 v60, 16, v183
	v_and_b32_e32 v61, 0xffff0000, v183
	v_lshlrev_b32_e32 v78, 16, v184
	v_and_b32_e32 v79, 0xffff0000, v184
	v_lshlrev_b32_e32 v62, 16, v185
	v_and_b32_e32 v63, 0xffff0000, v185
	v_pk_fma_f32 v[52:53], v[6:7], v[26:27], v[68:69]
	v_pk_fma_f32 v[54:55], v[8:9], v[28:29], v[70:71]
	v_pk_fma_f32 v[56:57], v[2:3], v[30:31], v[72:73]
	v_pk_fma_f32 v[58:59], v[4:5], v[32:33], v[74:75]
	v_pk_mul_f32 v[54:55], v[54:55], v[60:61]
	v_pk_mul_f32 v[52:53], v[52:53], v[76:77]
	v_pk_mul_f32 v[58:59], v[58:59], v[62:63]
	v_pk_mul_f32 v[56:57], v[56:57], v[78:79]
	v_cvt_pk_bf16_f32 v52, v52, v53
	v_cvt_pk_bf16_f32 v53, v54, v55
	v_cvt_pk_bf16_f32 v54, v56, v57
	v_cvt_pk_bf16_f32 v55, v58, v59
	global_store_dwordx4 v[66:67], v[52:55], off
	v_add_co_u32_e32 v56, vcc, s5, v36
	s_nop 0
	v_addc_co_u32_e32 v57, vcc, 0, v37, vcc
	s_nop 0
	v_pk_mul_f32 v[22:23], v[22:23], v[26:27]
	v_pk_mul_f32 v[24:25], v[24:25], v[28:29]
	v_pk_mul_f32 v[18:19], v[18:19], v[30:31]
	v_pk_mul_f32 v[20:21], v[20:21], v[32:33]
	v_pk_fma_f32 v[24:25], v[16:17], v[38:39], v[24:25]
	v_pk_fma_f32 v[22:23], v[14:15], v[40:41], v[22:23]
	v_pk_fma_f32 v[20:21], v[12:13], v[48:49], v[20:21]
	v_pk_fma_f32 v[18:19], v[10:11], v[50:51], v[18:19]
	s_add_i32 s5, s22, 8
	s_cmp_lg_u32 s5, s21
	v_lshlrev_b32_e32 v10, 16, v186
	v_and_b32_e32 v11, 0xffff0000, v186
	v_lshlrev_b32_e32 v12, 16, v187
	v_and_b32_e32 v13, 0xffff0000, v187
	v_lshlrev_b32_e32 v14, 16, v188
	v_and_b32_e32 v15, 0xffff0000, v188
	v_lshlrev_b32_e32 v16, 16, v189
	v_and_b32_e32 v17, 0xffff0000, v189
	v_lshlrev_b32_e32 v38, 16, v190
	v_and_b32_e32 v39, 0xffff0000, v190
	v_lshlrev_b32_e32 v40, 16, v191
	v_and_b32_e32 v41, 0xffff0000, v191
	v_lshlrev_b32_e32 v48, 16, v192
	v_and_b32_e32 v49, 0xffff0000, v192
	v_lshlrev_b32_e32 v50, 16, v193
	v_and_b32_e32 v51, 0xffff0000, v193
	v_pk_mul_f32 v[12:13], v[12:13], v[40:41]
	v_pk_mul_f32 v[10:11], v[10:11], v[38:39]
	v_pk_mul_f32 v[16:17], v[16:17], v[50:51]
	v_pk_mul_f32 v[14:15], v[14:15], v[48:49]
	v_lshlrev_b32_e32 v52, 16, v194
	v_and_b32_e32 v53, 0xffff0000, v194
	v_lshlrev_b32_e32 v54, 16, v195
	v_and_b32_e32 v55, 0xffff0000, v195
	v_lshlrev_b32_e32 v56, 16, v196
	v_and_b32_e32 v57, 0xffff0000, v196
	v_lshlrev_b32_e32 v58, 16, v197
	v_and_b32_e32 v59, 0xffff0000, v197
	v_pk_fma_f32 v[6:7], v[6:7], v[10:11], v[22:23]
	v_pk_fma_f32 v[8:9], v[8:9], v[12:13], v[24:25]
	v_pk_fma_f32 v[2:3], v[2:3], v[14:15], v[18:19]
	v_pk_fma_f32 v[4:5], v[4:5], v[16:17], v[20:21]
	v_pk_mul_f32 v[8:9], v[8:9], v[54:55]
	v_pk_mul_f32 v[6:7], v[6:7], v[52:53]
	v_pk_mul_f32 v[18:19], v[4:5], v[58:59]
	v_pk_mul_f32 v[4:5], v[2:3], v[56:57]
	v_cvt_pk_bf16_f32 v2, v6, v7
	v_cvt_pk_bf16_f32 v3, v8, v9
	v_cvt_pk_bf16_f32 v4, v4, v5
	v_cvt_pk_bf16_f32 v5, v18, v19
	global_store_dwordx4 v[46:47], v[2:5], off
	s_cbranch_scc1 .LBB0_685
; __device__ __forceinline__ void unpack8(u32x4 w, f32x4& a, f32x4& b) { a = (f32x4){bf_lo(w.x), bf_hi(w.x), bf_lo(w.y), bf_hi(w.y)}; b = (f32x4){bf_lo(w.z), bf_hi(w.z), bf_lo(w.w), bf_hi(w.w)}; }
; __device__ __forceinline__ void sconv_item(const Args& args, int l, int item, int lane) {
;     ...
;     if (t0 + 8 == T) {
;         float* so = smp ? args.out + O_SSC + ((size_t)l * DBATCH + b) * 2 * LW + c0 : args.out + O_PSC + ((size_t)l * NBATCH + b) * 2 * LW + c0;
;         *(f32x4*)so = zm2[0]; *(f32x4*)(so + 4) = zm2[1]; *(f32x4*)(so + LW) = zm1[0]; *(f32x4*)(so + LW + 4) = zm1[1];
;         float* lo = smp ? args.out + O_SLC + ((size_t)l * DBATCH + b) * 3 * LW + c0 : args.out + O_PLC + ((size_t)l * NBATCH + b) * 3 * LW + c0;
; #pragma unroll
;         for (int k = 0; k < 3; ++k) { f32x4 x0, x1; unpack8(*(const u32x4*)(PROJ + (size_t)(row0 + 5 + k) * INC + C_LX + c0), x0, x1); *(f32x4*)(lo + k * LW) = x0; *(f32x4*)(lo + k * LW + 4) = x1; }
;     }
	s_ashr_i32 s5, s4, 31
	s_lshl_b64 s[8:9], s[4:5], 13
	s_and_b64 s[16:17], s[0:1], exec
	s_mov_b32 s7, 0x9a30000
	v_readlane_b32 s52, v249, 12
	s_cselect_b32 s7, s7, 0x8820000
	v_readlane_b32 s64, v249, 24
	v_readlane_b32 s65, v249, 25
	s_add_u32 s7, s64, s7
	s_addc_u32 s21, s65, 0
	s_and_b64 s[16:17], s[0:1], exec
	v_readlane_b32 s22, v255, 39
	s_cselect_b32 s16, 18, 14
	v_readlane_b32 s23, v255, 40
	s_lshl_b64 s[16:17], s[22:23], s16
	s_add_u32 s7, s7, s16
	s_addc_u32 s16, s21, s17
	s_add_u32 s8, s7, s8
	s_addc_u32 s9, s16, s9
	v_lshlrev_b64 v[6:7], 2, v[42:43]
	v_lshl_add_u64 v[2:3], s[8:9], 0, v[6:7]
	s_movk_i32 s16, 0x1000
	global_store_dwordx4 v[2:3], v[26:29], off
	global_store_dwordx4 v[2:3], v[30:33], off offset:16
	v_add_co_u32_e32 v2, vcc, s16, v2
	s_and_b64 s[8:9], s[0:1], exec
	s_nop 0
	v_addc_co_u32_e32 v3, vcc, 0, v3, vcc
	global_store_dwordx4 v[2:3], v[10:13], off
	global_store_dwordx4 v[2:3], v[14:17], off offset:16
	global_load_dwordx4 v[2:5], v[34:35], off
	s_mov_b32 s7, 0x98b0000
	s_cselect_b32 s7, s7, 0x8808000
	s_add_u32 s7, s64, s7
	s_addc_u32 s8, s65, 0
	s_and_b64 s[0:1], s[0:1], exec
	s_cselect_b32 s0, 5, 1
	s_lshl_b64 s[0:1], s[22:23], s0
	s_add_u32 s0, s0, s4
	s_addc_u32 s1, s1, s5
	s_mul_hi_u32 s4, s0, 0x3000
	s_mulk_i32 s1, 0x3000
	s_mulk_i32 s0, 0x3000
	s_add_i32 s4, s4, s1
	s_add_u32 s0, s7, s0
	s_addc_u32 s1, s8, s4
	s_add_i32 s4, s6, 1
	v_lshl_add_u64 v[10:11], s[0:1], 0, v[6:7]
	v_mad_i64_i32 v[12:13], s[0:1], s4, v206, v[44:45]
	v_readlane_b32 s53, v249, 13
	v_readlane_b32 s54, v249, 14
	v_readlane_b32 s55, v249, 15
	v_readlane_b32 s56, v249, 16
	v_readlane_b32 s57, v249, 17
	v_readlane_b32 s58, v249, 18
	v_readlane_b32 s59, v249, 19
	v_readlane_b32 s60, v249, 20
	v_readlane_b32 s61, v249, 21
	v_readlane_b32 s62, v249, 22
	v_readlane_b32 s63, v249, 23
	v_readlane_b32 s66, v249, 26
	v_readlane_b32 s67, v249, 27
	s_waitcnt vmcnt(0)
	v_lshlrev_b32_e32 v6, 16, v2
	v_and_b32_e32 v7, 0xffff0000, v2
	v_lshlrev_b32_e32 v8, 16, v3
	v_and_b32_e32 v9, 0xffff0000, v3
	v_lshlrev_b32_e32 v2, 16, v4
	v_and_b32_e32 v3, 0xffff0000, v4
	v_lshlrev_b32_e32 v4, 16, v5
	v_and_b32_e32 v5, 0xffff0000, v5
	global_store_dwordx4 v[10:11], v[6:9], off
	global_store_dwordx4 v[10:11], v[2:5], off offset:16
	global_load_dwordx4 v[2:5], v[12:13], off
	v_add_co_u32_e32 v12, vcc, s16, v10
	s_waitcnt vmcnt(0)
	v_lshlrev_b32_e32 v6, 16, v2
	v_addc_co_u32_e32 v13, vcc, 0, v11, vcc
	v_and_b32_e32 v7, 0xffff0000, v2
	v_lshlrev_b32_e32 v8, 16, v3
	v_and_b32_e32 v9, 0xffff0000, v3
	v_lshlrev_b32_e32 v2, 16, v4
	v_and_b32_e32 v3, 0xffff0000, v4
	v_lshlrev_b32_e32 v4, 16, v5
	v_and_b32_e32 v5, 0xffff0000, v5
	global_store_dwordx4 v[12:13], v[6:9], off
	global_store_dwordx4 v[12:13], v[2:5], off offset:16
	global_load_dwordx4 v[2:5], v[36:37], off
	v_add_co_u32_e32 v10, vcc, 0x2000, v10
	s_waitcnt vmcnt(0)
	v_lshlrev_b32_e32 v6, 16, v2
	v_addc_co_u32_e32 v11, vcc, 0, v11, vcc
	v_and_b32_e32 v7, 0xffff0000, v2
	v_lshlrev_b32_e32 v8, 16, v3
	v_and_b32_e32 v9, 0xffff0000, v3
	v_lshlrev_b32_e32 v2, 16, v4
	v_and_b32_e32 v3, 0xffff0000, v4
	v_lshlrev_b32_e32 v4, 16, v5
	v_and_b32_e32 v5, 0xffff0000, v5
	global_store_dwordx4 v[10:11], v[6:9], off
	global_store_dwordx4 v[10:11], v[2:5], off offset:16
	s_branch .LBB0_685
